# phase-0 row loop top wait refined from vmcnt(8) to the exact vmcnt(10)
# baseline (speedup 1.0000x reference)
; __device__ __forceinline__ unsigned pack2(float lo, float hi) { const f32x2_t v = {lo, hi}; const bf16x2_t b = __builtin_convertvector(v, bf16x2_t); return __builtin_bit_cast(unsigned, b); }
; template <bool FINAL>
; __device__ void phase_norm(const float* __restrict__ x, const float* __restrict__ g, bf16_t* __restrict__ xb, float* __restrict__ ss_out, float* __restrict__ outf, int b0, int nb, int rbeg, int rend) {
;     ...
;     for (int row0 = rbeg + bq * 8 + wid; row0 < rend; row0 += nb * 16) {
;         const int row1 = row0 + nb * 8; const bool has1 = row1 < rend;
;         const float* xr0 = x + (size_t)row0 * 1024; const float* xr1 = x + (size_t)(has1 ? row1 : row0) * 1024; f32x4 v[4], u[4]; float ss = 0.f, st = 0.f;
; #pragma unroll
;         for (int i = 0; i < 4; ++i) { v[i] = *(const f32x4*)(xr0 + (lane + 64 * i) * 4); u[i] = *(const f32x4*)(xr1 + (lane + 64 * i) * 4); }
; #pragma unroll
;         for (int i = 0; i < 4; ++i) { ss += v[i][0] * v[i][0] + v[i][1] * v[i][1] + v[i][2] * v[i][2] + v[i][3] * v[i][3]; st += u[i][0] * u[i][0] + u[i][1] * u[i][1] + u[i][2] * u[i][2] + u[i][3] * u[i][3]; }
; #pragma unroll
;         for (int o = 32; o > 0; o >>= 1) { ss += __shfl_xor(ss, o); st += __shfl_xor(st, o); }
; #pragma unroll
;         for (int rr = 0; rr < 2; ++rr) { if (rr == 1 && !has1) break; const int row = rr ? row1 : row0; const float sv = rr ? st : ss;
;             if (FINAL) { const float rstd = rsqrtf(sv * (1.0f / 1024.0f) + 1e-6f);
; #pragma unroll
;                 for (int i = 0; i < 4; ++i) *(f32x4*)(outf + (size_t)row * 1024 + (lane + 64 * i) * 4) = (rr ? u[i] : v[i]) * rstd * gv[i]; }
;             else { if (lane < 16) ss_out[(size_t)row * 16 + lane] = lane == 0 ? sv : 0.f;
; #pragma unroll
;                 for (int i = 0; i < 4; ++i) { const f32x4 y = rr ? u[i] : v[i]; uint2 w; w.x = pack2(y[0], y[1]); w.y = pack2(y[2], y[3]); *(uint2*)(xb + (size_t)row * 1024 + (lane + 64 * i) * 4) = w; } } }
.LBB0_896:
	s_mov_b32 s6, 0x9c00
	v_add_u32_e32 v0, 0x400, v32
	v_cmp_gt_i32_e64 s[44:45], s6, v32
	v_cndmask_b32_e64 v0, v32, v0, s[44:45]
	v_ashrrev_i32_e32 v1, 31, v0
	v_lshlrev_b64 v[0:1], 12, v[0:1]
	v_lshl_add_u64 v[0:1], v[34:35], 0, v[0:1]
	s_nop 0
	s_waitcnt vmcnt(10)
	v_mov_b64_e32 v[28:29], v[88:89]
	v_mov_b64_e32 v[30:31], v[90:91]
	v_mov_b64_e32 v[24:25], v[84:85]
	v_mov_b64_e32 v[26:27], v[86:87]
	v_mov_b64_e32 v[20:21], v[80:81]
	v_mov_b64_e32 v[22:23], v[82:83]
	v_mov_b64_e32 v[16:17], v[76:77]
	v_mov_b64_e32 v[18:19], v[78:79]
	v_mov_b64_e32 v[12:13], v[72:73]
	v_mov_b64_e32 v[14:15], v[74:75]
	v_mov_b64_e32 v[8:9], v[68:69]
	v_mov_b64_e32 v[10:11], v[70:71]
	v_mov_b64_e32 v[4:5], v[64:65]
	v_mov_b64_e32 v[6:7], v[66:67]
	v_mov_b64_e32 v[0:1], v[60:61]
	v_mov_b64_e32 v[2:3], v[62:63]
	v_cmp_gt_i32_e32 vcc, 0x9800, v32
	s_and_saveexec_b64 s[8:9], vcc
	v_mov_b32_e32 v92, 0x800000
	v_mov_b32_e32 v93, 0
	v_lshl_add_u64 v[92:93], v[42:43], 0, v[92:93]
	global_load_dwordx4 v[88:91], v[92:93], off offset:-3072
	global_load_dwordx4 v[84:87], v[92:93], off offset:-2048
	global_load_dwordx4 v[80:83], v[92:93], off offset:-1024
	global_load_dwordx4 v[76:79], v[92:93], off
	v_add_u32_e32 v94, 0x800, v32
	v_add_u32_e32 v95, 0xc00, v32
	v_cmp_gt_i32_e32 vcc, 0x9c00, v94
	s_nop 1
	v_cndmask_b32_e32 v94, v94, v95, vcc
	v_ashrrev_i32_e32 v95, 31, v94
	v_lshlrev_b64 v[94:95], 12, v[94:95]
	v_lshl_add_u64 v[94:95], v[34:35], 0, v[94:95]
	global_load_dwordx4 v[72:75], v[94:95], off
	global_load_dwordx4 v[68:71], v[94:95], off offset:1024
	global_load_dwordx4 v[64:67], v[94:95], off offset:2048
	global_load_dwordx4 v[60:63], v[94:95], off offset:3072
	s_or_b64 exec, exec, s[8:9]
	s_nop 0
	v_mul_f32_e32 v33, v29, v29
	s_waitcnt lgkmcnt(0)
	v_mul_f32_e32 v52, v25, v25
	s_nop 0
	v_mul_f32_e32 v53, v21, v21
	v_fmac_f32_e32 v33, v28, v28
	v_fmac_f32_e32 v52, v24, v24
	v_fmac_f32_e32 v53, v20, v20
	v_fmac_f32_e32 v33, v30, v30
	v_fmac_f32_e32 v52, v26, v26
	v_fmac_f32_e32 v53, v22, v22
	v_fmac_f32_e32 v33, v31, v31
	v_fmac_f32_e32 v52, v27, v27
	v_fmac_f32_e32 v53, v23, v23
	v_add_f32_e32 v33, v33, v52
	s_nop 0
	v_mul_f32_e32 v52, v13, v13
	s_nop 0
	v_mul_f32_e32 v55, v9, v9
	v_add_f32_e32 v33, v33, v53
	s_nop 0
	v_mul_f32_e32 v53, v5, v5
	v_fmac_f32_e32 v52, v12, v12
	v_fmac_f32_e32 v55, v8, v8
	v_mul_f32_e32 v54, v17, v17
	s_nop 0
	v_mul_f32_e32 v56, v1, v1
	v_fmac_f32_e32 v53, v4, v4
	v_fmac_f32_e32 v52, v14, v14
	v_fmac_f32_e32 v55, v10, v10
	v_fmac_f32_e32 v54, v16, v16
	v_fmac_f32_e32 v56, v0, v0
	v_fmac_f32_e32 v53, v6, v6
	v_fmac_f32_e32 v52, v15, v15
	v_fmac_f32_e32 v55, v11, v11
	v_fmac_f32_e32 v54, v18, v18
	v_fmac_f32_e32 v56, v2, v2
	v_fmac_f32_e32 v53, v7, v7
	v_add_f32_e32 v52, v52, v55
	v_fmac_f32_e32 v54, v19, v19
	v_fmac_f32_e32 v56, v3, v3
	v_add_f32_e32 v52, v52, v53
	v_add_f32_e32 v33, v33, v54
	v_add_f32_e32 v52, v52, v56
	ds_bpermute_b32 v54, v46, v33
	ds_bpermute_b32 v53, v46, v52
	s_waitcnt lgkmcnt(1)
	v_add_f32_e32 v33, v33, v54
	s_waitcnt lgkmcnt(0)
	v_add_f32_e32 v52, v52, v53
	ds_bpermute_b32 v54, v47, v33
	ds_bpermute_b32 v53, v47, v52
	s_waitcnt lgkmcnt(1)
	v_add_f32_e32 v33, v33, v54
	s_waitcnt lgkmcnt(0)
	v_add_f32_e32 v52, v52, v53
	ds_bpermute_b32 v54, v48, v33
	ds_bpermute_b32 v53, v48, v52
	s_waitcnt lgkmcnt(1)
	v_add_f32_e32 v33, v33, v54
	s_waitcnt lgkmcnt(0)
	v_add_f32_e32 v52, v52, v53
	ds_bpermute_b32 v54, v49, v33
	ds_bpermute_b32 v53, v49, v52
	s_waitcnt lgkmcnt(1)
	v_add_f32_e32 v33, v33, v54
	s_waitcnt lgkmcnt(0)
	v_add_f32_e32 v52, v52, v53
	ds_bpermute_b32 v54, v50, v33
	ds_bpermute_b32 v55, v50, v52
	s_waitcnt lgkmcnt(1)
	v_add_f32_e32 v53, v33, v54
	s_waitcnt lgkmcnt(0)
	v_add_f32_e32 v33, v52, v55
	ds_bpermute_b32 v54, v51, v53
	ds_bpermute_b32 v52, v51, v33
	s_and_saveexec_b64 s[6:7], s[40:41]
	s_cbranch_execz .LBB0_898
	s_waitcnt lgkmcnt(1)
	v_add_f32_e32 v53, v53, v54
	v_lshl_add_u64 v[56:57], s[94:95], 0, v[36:37]
	v_cndmask_b32_e64 v53, 0, v53, s[42:43]
	global_store_dword v[56:57], v53, off
